# gmlp tile hand-written: both K-tiles staged at once, epilogue operands (Y,U,bias) loaded ahead of the MFMAs instead of one round trip per row group
# speedup vs baseline: 1.0130x; 1.0063x over previous
.LBB0_254:
	s_and_b32 s20, s88, 7
	s_add_i32 s24, s88, 0xfffff800
	s_lshr_b32 s25, s24, 3
	s_lshl_b32 s32, s20, 15
	s_add_u32 s8, s50, s32
	s_addc_u32 s9, s51, 0
	s_add_u32 s8, s8, 0x1080000
	s_addc_u32 s9, s9, 0
	s_lshl_b32 s32, s24, 15
	s_add_u32 s10, s48, s32
	s_addc_u32 s11, s49, 0
	s_add_u32 s10, s10, 0x2000000
	s_addc_u32 s11, s11, 0
	s_lshl_b32 s20, s20, 8
	s_lshl_b32 s32, s25, 19
	s_add_i32 s32, s32, s20
	s_add_u32 s12, s50, s32
	s_addc_u32 s13, s51, 0
	s_add_u32 s12, s12, 0x5a00000
	s_addc_u32 s13, s13, 0
	s_mov_b32 s82, s12
	s_mov_b32 s83, s13
	s_lshl_b32 s32, s25, 18
	s_add_i32 s32, s32, s20
	s_add_u32 s14, s48, s32
	s_addc_u32 s15, s49, 0
	s_lshl_b32 s32, s20, 1
	s_add_u32 s80, s54, s32
	s_addc_u32 s81, s55, 0
	v_lshrrev_b32_e32 v73, 4, v129
	v_and_b32_e32 v0, 15, v73
	v_bfe_u32 v1, v73, 4, 2
	v_bfe_u32 v2, v73, 1, 3
	v_xor_b32_e32 v2, v1, v2
	v_lshlrev_b32_e32 v2, 4, v2
	v_lshl_or_b32 v89, v0, 7, v2
	v_xor_b32_e32 v91, 64, v89
	v_lshrrev_b32_e32 v2, 6, v73
	v_lshl_add_u32 v85, v2, 12, v89
	v_lshl_add_u32 v87, v2, 12, v91
	v_bfe_u32 v3, v73, 4, 3
	v_and_b32_e32 v4, 7, v73
	v_xor_b32_e32 v3, v3, v4
	v_lshlrev_b32_e32 v3, 4, v3
	v_lshrrev_b32_e32 v4, 3, v73
	v_lshl_or_b32 v93, v4, 8, v3
	v_add_u32_e32 v173, 8192, v93
	v_add_u32_e32 v234, 16384, v93
	v_add_u32_e32 v235, 24576, v93
	v_lshl_add_u32 v5, v2, 5, v1
	v_lshlrev_b32_e32 v6, 4, v0
	v_lshl_add_u32 v236, v5, 12, v6
	v_lshl_add_u32 v237, v5, 11, v6
	v_lshlrev_b32_e32 v238, 2, v5
	v_lshlrev_b32_e32 v5, 13, v2
	v_lshl_add_u32 v6, v1, 3, v0
	v_lshl_add_u32 v7, v1, 11, v5
	v_lshl_add_u32 v239, v6, 2, v7
	v_add_u32_e32 v8, 0x60, v6
	v_and_b32_e32 v8, 0x7f, v8
	v_lshl_add_u32 v240, v8, 2, v7
	v_add_u32_e32 v8, 0x70, v6
	v_and_b32_e32 v8, 0x7f, v8
	v_lshl_add_u32 v241, v8, 2, v7
	v_lshlrev_b32_e32 v8, 3, v0
	v_lshl_add_u32 v10, v1, 9, v5
	v_add_u32_e32 v9, 0, v8
	v_and_b32_e32 v9, 0x7f, v9
	v_lshl_add_u32 v242, v9, 2, v10
	v_add_u32_e32 v9, 8, v8
	v_and_b32_e32 v9, 0x7f, v9
	v_lshl_add_u32 v243, v9, 2, v10
	v_add_u32_e32 v243, 2048, v243
	v_add_u32_e32 v9, 16, v8
	v_and_b32_e32 v9, 0x7f, v9
	v_lshl_add_u32 v244, v9, 2, v10
	v_add_u32_e32 v244, 4096, v244
	v_add_u32_e32 v9, 24, v8
	v_and_b32_e32 v9, 0x7f, v9
	v_lshl_add_u32 v245, v9, 2, v10
	v_add_u32_e32 v245, 6144, v245
	v_readfirstlane_b32 s89, v129
	s_barrier
	s_add_u32 m0, s89, 0
	v_mov_b32_e32 v0, 0
	v_mov_b32_e32 v1, 0
	global_load_lds_dwordx4 v93, s[8:9]
	s_add_u32 m0, s89, 4096
	v_mov_b32_e32 v2, 0
	v_mov_b32_e32 v3, 0
	global_load_lds_dwordx4 v173, s[8:9]
	s_add_u32 m0, s89, 8192
	v_mov_b32_e32 v4, 0
	v_mov_b32_e32 v5, 0
	global_load_lds_dwordx4 v234, s[8:9]
	s_add_u32 m0, s89, 12288
	v_mov_b32_e32 v6, 0
	v_mov_b32_e32 v7, 0
	global_load_lds_dwordx4 v235, s[8:9]
	s_add_u32 s8, s8, 128
	s_addc_u32 s9, s9, 0
	s_add_u32 m0, s89, 16384
	v_mov_b32_e32 v8, 0
	v_mov_b32_e32 v9, 0
	global_load_lds_dwordx4 v93, s[10:11]
	s_add_u32 m0, s89, 20480
	v_mov_b32_e32 v10, 0
	v_mov_b32_e32 v11, 0
	global_load_lds_dwordx4 v173, s[10:11]
	s_add_u32 m0, s89, 24576
	v_mov_b32_e32 v12, 0
	v_mov_b32_e32 v13, 0
	global_load_lds_dwordx4 v234, s[10:11]
	s_add_u32 m0, s89, 28672
	v_mov_b32_e32 v14, 0
	v_mov_b32_e32 v15, 0
	global_load_lds_dwordx4 v235, s[10:11]
	s_add_u32 s10, s10, 128
	s_addc_u32 s11, s11, 0
	s_add_u32 m0, s89, 32768
	v_mov_b32_e32 v16, 0
	v_mov_b32_e32 v17, 0
	global_load_lds_dwordx4 v93, s[8:9]
	s_add_u32 m0, s89, 36864
	v_mov_b32_e32 v18, 0
	v_mov_b32_e32 v19, 0
	global_load_lds_dwordx4 v173, s[8:9]
	s_add_u32 m0, s89, 40960
	v_mov_b32_e32 v20, 0
	v_mov_b32_e32 v21, 0
	global_load_lds_dwordx4 v234, s[8:9]
	s_add_u32 m0, s89, 45056
	v_mov_b32_e32 v22, 0
	v_mov_b32_e32 v23, 0
	global_load_lds_dwordx4 v235, s[8:9]
	s_add_u32 m0, s89, 49152
	v_mov_b32_e32 v24, 0
	v_mov_b32_e32 v25, 0
	global_load_lds_dwordx4 v93, s[10:11]
	s_add_u32 m0, s89, 53248
	v_mov_b32_e32 v26, 0
	v_mov_b32_e32 v27, 0
	global_load_lds_dwordx4 v173, s[10:11]
	s_add_u32 m0, s89, 57344
	v_mov_b32_e32 v28, 0
	v_mov_b32_e32 v29, 0
	global_load_lds_dwordx4 v234, s[10:11]
	s_add_u32 m0, s89, 61440
	v_mov_b32_e32 v30, 0
	v_mov_b32_e32 v31, 0
	global_load_lds_dwordx4 v235, s[10:11]
	global_load_dwordx4 v[198:201], v236, s[12:13]
	global_load_dwordx4 v[214:217], v237, s[14:15]
	global_load_dword v230, v238, s[80:81] offset:0
	s_add_u32 s12, s12, 0x4000
	s_addc_u32 s13, s13, 0
	s_add_u32 s14, s14, 0x2000
	s_addc_u32 s15, s15, 0
	global_load_dwordx4 v[202:205], v236, s[12:13]
	global_load_dwordx4 v[218:221], v237, s[14:15]
	global_load_dword v231, v238, s[80:81] offset:16
	s_add_u32 s12, s12, 0x4000
	s_addc_u32 s13, s13, 0
	s_add_u32 s14, s14, 0x2000
	s_addc_u32 s15, s15, 0
	global_load_dwordx4 v[206:209], v236, s[12:13]
	global_load_dwordx4 v[222:225], v237, s[14:15]
	global_load_dword v232, v238, s[80:81] offset:32
	s_add_u32 s12, s12, 0x4000
	s_addc_u32 s13, s13, 0
	s_add_u32 s14, s14, 0x2000
	s_addc_u32 s15, s15, 0
	global_load_dwordx4 v[210:213], v236, s[12:13]
	global_load_dwordx4 v[226:229], v237, s[14:15]
	global_load_dword v233, v238, s[80:81] offset:48
	s_add_u32 s12, s12, 0x4000
	s_addc_u32 s13, s13, 0
	s_add_u32 s14, s14, 0x2000
	s_addc_u32 s15, s15, 0
	v_mov_b32_e32 v32, 0
	v_mov_b32_e32 v33, 0
	v_mov_b32_e32 v34, 0
	v_mov_b32_e32 v35, 0
	v_mov_b32_e32 v36, 0
	v_mov_b32_e32 v37, 0
	v_mov_b32_e32 v38, 0
	v_mov_b32_e32 v39, 0
	v_mov_b32_e32 v40, 0
	v_mov_b32_e32 v41, 0
	v_mov_b32_e32 v42, 0
	v_mov_b32_e32 v43, 0
	v_mov_b32_e32 v44, 0
	v_mov_b32_e32 v45, 0
	v_mov_b32_e32 v46, 0
	v_mov_b32_e32 v47, 0
	v_mov_b32_e32 v48, 0
	v_mov_b32_e32 v49, 0
	v_mov_b32_e32 v50, 0
	v_mov_b32_e32 v51, 0
	v_mov_b32_e32 v52, 0
	v_mov_b32_e32 v53, 0
	v_mov_b32_e32 v54, 0
	v_mov_b32_e32 v55, 0
	v_mov_b32_e32 v56, 0
	v_mov_b32_e32 v57, 0
	v_mov_b32_e32 v58, 0
	v_mov_b32_e32 v59, 0
	v_mov_b32_e32 v60, 0
	v_mov_b32_e32 v61, 0
	v_mov_b32_e32 v62, 0
	v_mov_b32_e32 v63, 0
	s_waitcnt vmcnt(12)
	s_barrier
	ds_read_b128 v[64:67], v85 offset:0
	ds_read_b128 v[68:71], v85 offset:2048
	ds_read_b128 v[174:177], v89 offset:16384
	ds_read_b128 v[178:181], v89 offset:18432
	ds_read_b128 v[182:185], v89 offset:20480
	ds_read_b128 v[186:189], v89 offset:22528
	ds_read_b128 v[190:193], v89 offset:24576
	ds_read_b128 v[194:197], v89 offset:26624
	s_waitcnt lgkmcnt(5)
	v_mfma_f32_16x16x32_bf16 v[0:3], v[64:67], v[174:177], v[0:3]
	v_mfma_f32_16x16x32_bf16 v[32:35], v[68:71], v[174:177], v[32:35]
	ds_read_b128 v[174:177], v89 offset:28672
	s_waitcnt lgkmcnt(5)
	v_mfma_f32_16x16x32_bf16 v[4:7], v[64:67], v[178:181], v[4:7]
	v_mfma_f32_16x16x32_bf16 v[36:39], v[68:71], v[178:181], v[36:39]
	ds_read_b128 v[178:181], v89 offset:30720
	s_waitcnt lgkmcnt(5)
	v_mfma_f32_16x16x32_bf16 v[8:11], v[64:67], v[182:185], v[8:11]
	v_mfma_f32_16x16x32_bf16 v[40:43], v[68:71], v[182:185], v[40:43]
	ds_read_b128 v[94:97], v87 offset:0
	ds_read_b128 v[98:101], v87 offset:2048
	ds_read_b128 v[182:185], v91 offset:16384
	s_waitcnt lgkmcnt(7)
	v_mfma_f32_16x16x32_bf16 v[12:15], v[64:67], v[186:189], v[12:15]
	v_mfma_f32_16x16x32_bf16 v[44:47], v[68:71], v[186:189], v[44:47]
	ds_read_b128 v[186:189], v91 offset:18432
	s_waitcnt lgkmcnt(7)
	v_mfma_f32_16x16x32_bf16 v[16:19], v[64:67], v[190:193], v[16:19]
	v_mfma_f32_16x16x32_bf16 v[48:51], v[68:71], v[190:193], v[48:51]
	ds_read_b128 v[190:193], v91 offset:20480
	s_waitcnt lgkmcnt(7)
	v_mfma_f32_16x16x32_bf16 v[20:23], v[64:67], v[194:197], v[20:23]
	v_mfma_f32_16x16x32_bf16 v[52:55], v[68:71], v[194:197], v[52:55]
	ds_read_b128 v[194:197], v91 offset:22528
	s_waitcnt lgkmcnt(7)
	v_mfma_f32_16x16x32_bf16 v[24:27], v[64:67], v[174:177], v[24:27]
	v_mfma_f32_16x16x32_bf16 v[56:59], v[68:71], v[174:177], v[56:59]
	ds_read_b128 v[174:177], v91 offset:24576
	s_waitcnt lgkmcnt(7)
	v_mfma_f32_16x16x32_bf16 v[28:31], v[64:67], v[178:181], v[28:31]
	v_mfma_f32_16x16x32_bf16 v[60:63], v[68:71], v[178:181], v[60:63]
	ds_read_b128 v[178:181], v91 offset:26624
	s_waitcnt lgkmcnt(5)
	v_mfma_f32_16x16x32_bf16 v[0:3], v[94:97], v[182:185], v[0:3]
	v_mfma_f32_16x16x32_bf16 v[32:35], v[98:101], v[182:185], v[32:35]
	ds_read_b128 v[182:185], v91 offset:28672
	s_waitcnt lgkmcnt(5)
	v_mfma_f32_16x16x32_bf16 v[4:7], v[94:97], v[186:189], v[4:7]
	v_mfma_f32_16x16x32_bf16 v[36:39], v[98:101], v[186:189], v[36:39]
	ds_read_b128 v[186:189], v91 offset:30720
	s_waitcnt lgkmcnt(5)
	v_mfma_f32_16x16x32_bf16 v[8:11], v[94:97], v[190:193], v[8:11]
	v_mfma_f32_16x16x32_bf16 v[40:43], v[98:101], v[190:193], v[40:43]
	ds_read_b128 v[64:67], v85 offset:32768
	ds_read_b128 v[68:71], v85 offset:34816
	ds_read_b128 v[190:193], v89 offset:49152
	s_waitcnt lgkmcnt(7)
	v_mfma_f32_16x16x32_bf16 v[12:15], v[94:97], v[194:197], v[12:15]
	v_mfma_f32_16x16x32_bf16 v[44:47], v[98:101], v[194:197], v[44:47]
	ds_read_b128 v[194:197], v89 offset:51200
	s_waitcnt lgkmcnt(7)
	v_mfma_f32_16x16x32_bf16 v[16:19], v[94:97], v[174:177], v[16:19]
	v_mfma_f32_16x16x32_bf16 v[48:51], v[98:101], v[174:177], v[48:51]
	ds_read_b128 v[174:177], v89 offset:53248
	s_waitcnt lgkmcnt(7)
	v_mfma_f32_16x16x32_bf16 v[20:23], v[94:97], v[178:181], v[20:23]
	v_mfma_f32_16x16x32_bf16 v[52:55], v[98:101], v[178:181], v[52:55]
	ds_read_b128 v[178:181], v89 offset:55296
	s_waitcnt lgkmcnt(7)
	v_mfma_f32_16x16x32_bf16 v[24:27], v[94:97], v[182:185], v[24:27]
	v_mfma_f32_16x16x32_bf16 v[56:59], v[98:101], v[182:185], v[56:59]
	ds_read_b128 v[182:185], v89 offset:57344
	s_waitcnt lgkmcnt(7)
	v_mfma_f32_16x16x32_bf16 v[28:31], v[94:97], v[186:189], v[28:31]
	v_mfma_f32_16x16x32_bf16 v[60:63], v[98:101], v[186:189], v[60:63]
	ds_read_b128 v[186:189], v89 offset:59392
	s_waitcnt lgkmcnt(5)
	v_mfma_f32_16x16x32_bf16 v[0:3], v[64:67], v[190:193], v[0:3]
	v_mfma_f32_16x16x32_bf16 v[32:35], v[68:71], v[190:193], v[32:35]
	ds_read_b128 v[190:193], v89 offset:61440
	s_waitcnt lgkmcnt(5)
	v_mfma_f32_16x16x32_bf16 v[4:7], v[64:67], v[194:197], v[4:7]
	v_mfma_f32_16x16x32_bf16 v[36:39], v[68:71], v[194:197], v[36:39]
	ds_read_b128 v[194:197], v89 offset:63488
	s_waitcnt lgkmcnt(5)
	v_mfma_f32_16x16x32_bf16 v[8:11], v[64:67], v[174:177], v[8:11]
	v_mfma_f32_16x16x32_bf16 v[40:43], v[68:71], v[174:177], v[40:43]
	ds_read_b128 v[94:97], v87 offset:32768
	ds_read_b128 v[98:101], v87 offset:34816
	ds_read_b128 v[174:177], v91 offset:49152
	s_waitcnt lgkmcnt(7)
	v_mfma_f32_16x16x32_bf16 v[12:15], v[64:67], v[178:181], v[12:15]
	v_mfma_f32_16x16x32_bf16 v[44:47], v[68:71], v[178:181], v[44:47]
	ds_read_b128 v[178:181], v91 offset:51200
	s_waitcnt lgkmcnt(7)
	v_mfma_f32_16x16x32_bf16 v[16:19], v[64:67], v[182:185], v[16:19]
	v_mfma_f32_16x16x32_bf16 v[48:51], v[68:71], v[182:185], v[48:51]
	ds_read_b128 v[182:185], v91 offset:53248
	s_waitcnt lgkmcnt(7)
	v_mfma_f32_16x16x32_bf16 v[20:23], v[64:67], v[186:189], v[20:23]
	v_mfma_f32_16x16x32_bf16 v[52:55], v[68:71], v[186:189], v[52:55]
	ds_read_b128 v[186:189], v91 offset:55296
	s_waitcnt lgkmcnt(7)
	v_mfma_f32_16x16x32_bf16 v[24:27], v[64:67], v[190:193], v[24:27]
	v_mfma_f32_16x16x32_bf16 v[56:59], v[68:71], v[190:193], v[56:59]
	ds_read_b128 v[190:193], v91 offset:57344
	s_waitcnt lgkmcnt(7)
	v_mfma_f32_16x16x32_bf16 v[28:31], v[64:67], v[194:197], v[28:31]
	v_mfma_f32_16x16x32_bf16 v[60:63], v[68:71], v[194:197], v[60:63]
	ds_read_b128 v[194:197], v91 offset:59392
	s_waitcnt lgkmcnt(5)
	v_mfma_f32_16x16x32_bf16 v[0:3], v[94:97], v[174:177], v[0:3]
	v_mfma_f32_16x16x32_bf16 v[32:35], v[98:101], v[174:177], v[32:35]
	ds_read_b128 v[174:177], v91 offset:61440
	s_waitcnt lgkmcnt(5)
	v_mfma_f32_16x16x32_bf16 v[4:7], v[94:97], v[178:181], v[4:7]
	v_mfma_f32_16x16x32_bf16 v[36:39], v[98:101], v[178:181], v[36:39]
	ds_read_b128 v[178:181], v91 offset:63488
	s_waitcnt lgkmcnt(5)
	v_mfma_f32_16x16x32_bf16 v[8:11], v[94:97], v[182:185], v[8:11]
	v_mfma_f32_16x16x32_bf16 v[40:43], v[98:101], v[182:185], v[40:43]
	s_waitcnt lgkmcnt(4)
	v_mfma_f32_16x16x32_bf16 v[12:15], v[94:97], v[186:189], v[12:15]
	v_mfma_f32_16x16x32_bf16 v[44:47], v[98:101], v[186:189], v[44:47]
	s_waitcnt lgkmcnt(3)
	v_mfma_f32_16x16x32_bf16 v[16:19], v[94:97], v[190:193], v[16:19]
	v_mfma_f32_16x16x32_bf16 v[48:51], v[98:101], v[190:193], v[48:51]
	s_waitcnt lgkmcnt(2)
	v_mfma_f32_16x16x32_bf16 v[20:23], v[94:97], v[194:197], v[20:23]
	v_mfma_f32_16x16x32_bf16 v[52:55], v[98:101], v[194:197], v[52:55]
	s_waitcnt lgkmcnt(1)
	v_mfma_f32_16x16x32_bf16 v[24:27], v[94:97], v[174:177], v[24:27]
	v_mfma_f32_16x16x32_bf16 v[56:59], v[98:101], v[174:177], v[56:59]
	s_waitcnt lgkmcnt(0)
	v_mfma_f32_16x16x32_bf16 v[28:31], v[94:97], v[178:181], v[28:31]
	v_mfma_f32_16x16x32_bf16 v[60:63], v[98:101], v[178:181], v[60:63]
	global_load_dwordx4 v[174:177], v236, s[12:13]
	global_load_dwordx4 v[190:193], v237, s[14:15]
	global_load_dword v94, v238, s[80:81] offset:64
	s_add_u32 s12, s12, 0x4000
	s_addc_u32 s13, s13, 0
	s_add_u32 s14, s14, 0x2000
	s_addc_u32 s15, s15, 0
	global_load_dwordx4 v[178:181], v236, s[12:13]
	global_load_dwordx4 v[194:197], v237, s[14:15]
	global_load_dword v95, v238, s[80:81] offset:80
	s_add_u32 s12, s12, 0x4000
	s_addc_u32 s13, s13, 0
	s_add_u32 s14, s14, 0x2000
	s_addc_u32 s15, s15, 0
	global_load_dwordx4 v[182:185], v236, s[12:13]
	global_load_dwordx4 v[64:67], v237, s[14:15]
	global_load_dword v96, v238, s[80:81] offset:96
	s_add_u32 s12, s12, 0x4000
	s_addc_u32 s13, s13, 0
	s_add_u32 s14, s14, 0x2000
	s_addc_u32 s15, s15, 0
	global_load_dwordx4 v[186:189], v236, s[12:13]
	global_load_dwordx4 v[68:71], v237, s[14:15]
	global_load_dword v97, v238, s[80:81] offset:112
	s_add_u32 s12, s12, 0x4000
	s_addc_u32 s13, s13, 0
	s_add_u32 s14, s14, 0x2000
	s_addc_u32 s15, s15, 0
	s_nop 7
	s_waitcnt lgkmcnt(0)
	s_barrier
	ds_write_b32 v239, v0 offset:0
	ds_write_b32 v239, v1 offset:512
	ds_write_b32 v239, v2 offset:1024
	ds_write_b32 v239, v3 offset:1536
	ds_write_b32 v239, v4 offset:64
	ds_write_b32 v239, v5 offset:576
	ds_write_b32 v239, v6 offset:1088
	ds_write_b32 v239, v7 offset:1600
	ds_write_b32 v239, v8 offset:128
	ds_write_b32 v239, v9 offset:640
	ds_write_b32 v239, v10 offset:1152
	ds_write_b32 v239, v11 offset:1664
	ds_write_b32 v239, v12 offset:192
	ds_write_b32 v239, v13 offset:704
	ds_write_b32 v239, v14 offset:1216
	ds_write_b32 v239, v15 offset:1728
	ds_write_b32 v239, v16 offset:256
	ds_write_b32 v239, v17 offset:768
	ds_write_b32 v239, v18 offset:1280
	ds_write_b32 v239, v19 offset:1792
	ds_write_b32 v239, v20 offset:320
	ds_write_b32 v239, v21 offset:832
	ds_write_b32 v239, v22 offset:1344
	ds_write_b32 v239, v23 offset:1856
	ds_write_b32 v240, v24 offset:0
	ds_write_b32 v240, v25 offset:512
	ds_write_b32 v240, v26 offset:1024
	ds_write_b32 v240, v27 offset:1536
	ds_write_b32 v241, v28 offset:0
	ds_write_b32 v241, v29 offset:512
	ds_write_b32 v241, v30 offset:1024
	ds_write_b32 v241, v31 offset:1536
	s_waitcnt lgkmcnt(0)
	ds_read_b128 v[0:3], v242
	ds_read_b128 v[4:7], v242 offset:16
	ds_read_b128 v[8:11], v243
	ds_read_b128 v[12:15], v243 offset:16
	ds_read_b128 v[16:19], v244
	ds_read_b128 v[20:23], v244 offset:16
	ds_read_b128 v[24:27], v245
	ds_read_b128 v[28:31], v245 offset:16
	s_waitcnt vmcnt(21) lgkmcnt(6)
	v_add_f32_e32 v0, v0, v230
	v_add_f32_e32 v1, v1, v230
	v_add_f32_e32 v2, v2, v230
	v_add_f32_e32 v3, v3, v230
	v_add_f32_e32 v4, v4, v230
	v_add_f32_e32 v5, v5, v230
	v_add_f32_e32 v6, v6, v230
	v_add_f32_e32 v7, v7, v230
	v_lshlrev_b32_e32 v98, 16, v214
	v_lshlrev_b32_e32 v99, 16, v215
	v_lshlrev_b32_e32 v100, 16, v216
	v_lshlrev_b32_e32 v101, 16, v217
	v_and_b32_e32 v214, 0xffff0000, v214
	v_and_b32_e32 v215, 0xffff0000, v215
	v_and_b32_e32 v216, 0xffff0000, v216
	v_and_b32_e32 v217, 0xffff0000, v217
	v_mul_f32_e32 v0, v0, v98
	v_mul_f32_e32 v1, v1, v214
	v_mul_f32_e32 v2, v2, v99
	v_mul_f32_e32 v3, v3, v215
	v_mul_f32_e32 v4, v4, v100
	v_mul_f32_e32 v5, v5, v216
	v_mul_f32_e32 v6, v6, v101
	v_mul_f32_e32 v7, v7, v217
	v_lshlrev_b32_e32 v98, 16, v198
	v_lshlrev_b32_e32 v99, 16, v199
	v_lshlrev_b32_e32 v100, 16, v200
	v_lshlrev_b32_e32 v101, 16, v201
	v_and_b32_e32 v198, 0xffff0000, v198
	v_and_b32_e32 v199, 0xffff0000, v199
	v_and_b32_e32 v200, 0xffff0000, v200
	v_and_b32_e32 v201, 0xffff0000, v201
	v_mul_f32_e32 v0, v0, v98
	v_mul_f32_e32 v1, v1, v198
	v_mul_f32_e32 v2, v2, v99
	v_mul_f32_e32 v3, v3, v199
	v_mul_f32_e32 v4, v4, v100
	v_mul_f32_e32 v5, v5, v200
	v_mul_f32_e32 v6, v6, v101
	v_mul_f32_e32 v7, v7, v201
	v_cvt_pk_bf16_f32 v0, v0, v1
	v_cvt_pk_bf16_f32 v1, v2, v3
	v_cvt_pk_bf16_f32 v2, v4, v5
	v_cvt_pk_bf16_f32 v3, v6, v7
	global_store_dwordx4 v236, v[0:3], s[82:83]
	s_add_u32 s82, s82, 0x4000
	s_addc_u32 s83, s83, 0
	s_waitcnt vmcnt(19) lgkmcnt(4)
	v_add_f32_e32 v8, v8, v231
	v_add_f32_e32 v9, v9, v231
	v_add_f32_e32 v10, v10, v231
	v_add_f32_e32 v11, v11, v231
	v_add_f32_e32 v12, v12, v231
	v_add_f32_e32 v13, v13, v231
	v_add_f32_e32 v14, v14, v231
	v_add_f32_e32 v15, v15, v231
	v_lshlrev_b32_e32 v98, 16, v218
	v_lshlrev_b32_e32 v99, 16, v219
	v_lshlrev_b32_e32 v100, 16, v220
	v_lshlrev_b32_e32 v101, 16, v221
	v_and_b32_e32 v218, 0xffff0000, v218
	v_and_b32_e32 v219, 0xffff0000, v219
	v_and_b32_e32 v220, 0xffff0000, v220
	v_and_b32_e32 v221, 0xffff0000, v221
	v_mul_f32_e32 v8, v8, v98
	v_mul_f32_e32 v9, v9, v218
	v_mul_f32_e32 v10, v10, v99
	v_mul_f32_e32 v11, v11, v219
	v_mul_f32_e32 v12, v12, v100
	v_mul_f32_e32 v13, v13, v220
	v_mul_f32_e32 v14, v14, v101
	v_mul_f32_e32 v15, v15, v221
	v_lshlrev_b32_e32 v98, 16, v202
	v_lshlrev_b32_e32 v99, 16, v203
	v_lshlrev_b32_e32 v100, 16, v204
	v_lshlrev_b32_e32 v101, 16, v205
	v_and_b32_e32 v202, 0xffff0000, v202
	v_and_b32_e32 v203, 0xffff0000, v203
	v_and_b32_e32 v204, 0xffff0000, v204
	v_and_b32_e32 v205, 0xffff0000, v205
	v_mul_f32_e32 v8, v8, v98
	v_mul_f32_e32 v9, v9, v202
	v_mul_f32_e32 v10, v10, v99
	v_mul_f32_e32 v11, v11, v203
	v_mul_f32_e32 v12, v12, v100
	v_mul_f32_e32 v13, v13, v204
	v_mul_f32_e32 v14, v14, v101
	v_mul_f32_e32 v15, v15, v205
	v_cvt_pk_bf16_f32 v8, v8, v9
	v_cvt_pk_bf16_f32 v9, v10, v11
	v_cvt_pk_bf16_f32 v10, v12, v13
	v_cvt_pk_bf16_f32 v11, v14, v15
	global_store_dwordx4 v236, v[8:11], s[82:83]
	s_add_u32 s82, s82, 0x4000
	s_addc_u32 s83, s83, 0
	s_waitcnt vmcnt(17) lgkmcnt(2)
	v_add_f32_e32 v16, v16, v232
	v_add_f32_e32 v17, v17, v232
	v_add_f32_e32 v18, v18, v232
	v_add_f32_e32 v19, v19, v232
	v_add_f32_e32 v20, v20, v232
	v_add_f32_e32 v21, v21, v232
	v_add_f32_e32 v22, v22, v232
	v_add_f32_e32 v23, v23, v232
	v_lshlrev_b32_e32 v98, 16, v222
	v_lshlrev_b32_e32 v99, 16, v223
	v_lshlrev_b32_e32 v100, 16, v224
	v_lshlrev_b32_e32 v101, 16, v225
	v_and_b32_e32 v222, 0xffff0000, v222
	v_and_b32_e32 v223, 0xffff0000, v223
	v_and_b32_e32 v224, 0xffff0000, v224
	v_and_b32_e32 v225, 0xffff0000, v225
	v_mul_f32_e32 v16, v16, v98
	v_mul_f32_e32 v17, v17, v222
	v_mul_f32_e32 v18, v18, v99
	v_mul_f32_e32 v19, v19, v223
	v_mul_f32_e32 v20, v20, v100
	v_mul_f32_e32 v21, v21, v224
	v_mul_f32_e32 v22, v22, v101
	v_mul_f32_e32 v23, v23, v225
	v_lshlrev_b32_e32 v98, 16, v206
	v_lshlrev_b32_e32 v99, 16, v207
	v_lshlrev_b32_e32 v100, 16, v208
	v_lshlrev_b32_e32 v101, 16, v209
	v_and_b32_e32 v206, 0xffff0000, v206
	v_and_b32_e32 v207, 0xffff0000, v207
	v_and_b32_e32 v208, 0xffff0000, v208
	v_and_b32_e32 v209, 0xffff0000, v209
	v_mul_f32_e32 v16, v16, v98
	v_mul_f32_e32 v17, v17, v206
	v_mul_f32_e32 v18, v18, v99
	v_mul_f32_e32 v19, v19, v207
	v_mul_f32_e32 v20, v20, v100
	v_mul_f32_e32 v21, v21, v208
	v_mul_f32_e32 v22, v22, v101
	v_mul_f32_e32 v23, v23, v209
	v_cvt_pk_bf16_f32 v16, v16, v17
	v_cvt_pk_bf16_f32 v17, v18, v19
	v_cvt_pk_bf16_f32 v18, v20, v21
	v_cvt_pk_bf16_f32 v19, v22, v23
	global_store_dwordx4 v236, v[16:19], s[82:83]
	s_add_u32 s82, s82, 0x4000
	s_addc_u32 s83, s83, 0
	s_waitcnt vmcnt(15) lgkmcnt(0)
	v_add_f32_e32 v24, v24, v233
	v_add_f32_e32 v25, v25, v233
	v_add_f32_e32 v26, v26, v233
	v_add_f32_e32 v27, v27, v233
	v_add_f32_e32 v28, v28, v233
	v_add_f32_e32 v29, v29, v233
	v_add_f32_e32 v30, v30, v233
	v_add_f32_e32 v31, v31, v233
	v_lshlrev_b32_e32 v98, 16, v226
	v_lshlrev_b32_e32 v99, 16, v227
	v_lshlrev_b32_e32 v100, 16, v228
	v_lshlrev_b32_e32 v101, 16, v229
	v_and_b32_e32 v226, 0xffff0000, v226
	v_and_b32_e32 v227, 0xffff0000, v227
	v_and_b32_e32 v228, 0xffff0000, v228
	v_and_b32_e32 v229, 0xffff0000, v229
	v_mul_f32_e32 v24, v24, v98
	v_mul_f32_e32 v25, v25, v226
	v_mul_f32_e32 v26, v26, v99
	v_mul_f32_e32 v27, v27, v227
	v_mul_f32_e32 v28, v28, v100
	v_mul_f32_e32 v29, v29, v228
	v_mul_f32_e32 v30, v30, v101
	v_mul_f32_e32 v31, v31, v229
	v_lshlrev_b32_e32 v98, 16, v210
	v_lshlrev_b32_e32 v99, 16, v211
	v_lshlrev_b32_e32 v100, 16, v212
	v_lshlrev_b32_e32 v101, 16, v213
	v_and_b32_e32 v210, 0xffff0000, v210
	v_and_b32_e32 v211, 0xffff0000, v211
	v_and_b32_e32 v212, 0xffff0000, v212
	v_and_b32_e32 v213, 0xffff0000, v213
	v_mul_f32_e32 v24, v24, v98
	v_mul_f32_e32 v25, v25, v210
	v_mul_f32_e32 v26, v26, v99
	v_mul_f32_e32 v27, v27, v211
	v_mul_f32_e32 v28, v28, v100
	v_mul_f32_e32 v29, v29, v212
	v_mul_f32_e32 v30, v30, v101
	v_mul_f32_e32 v31, v31, v213
	v_cvt_pk_bf16_f32 v24, v24, v25
	v_cvt_pk_bf16_f32 v25, v26, v27
	v_cvt_pk_bf16_f32 v26, v28, v29
	v_cvt_pk_bf16_f32 v27, v30, v31
	global_store_dwordx4 v236, v[24:27], s[82:83]
	s_add_u32 s82, s82, 0x4000
	s_addc_u32 s83, s83, 0
	ds_write_b32 v239, v32 offset:0
	ds_write_b32 v239, v33 offset:512
	ds_write_b32 v239, v34 offset:1024
	ds_write_b32 v239, v35 offset:1536
	ds_write_b32 v239, v36 offset:64
	ds_write_b32 v239, v37 offset:576
	ds_write_b32 v239, v38 offset:1088
	ds_write_b32 v239, v39 offset:1600
	ds_write_b32 v239, v40 offset:128
	ds_write_b32 v239, v41 offset:640
	ds_write_b32 v239, v42 offset:1152
	ds_write_b32 v239, v43 offset:1664
	ds_write_b32 v239, v44 offset:192
	ds_write_b32 v239, v45 offset:704
	ds_write_b32 v239, v46 offset:1216
	ds_write_b32 v239, v47 offset:1728
	ds_write_b32 v239, v48 offset:256
	ds_write_b32 v239, v49 offset:768
	ds_write_b32 v239, v50 offset:1280
	ds_write_b32 v239, v51 offset:1792
	ds_write_b32 v239, v52 offset:320
	ds_write_b32 v239, v53 offset:832
	ds_write_b32 v239, v54 offset:1344
	ds_write_b32 v239, v55 offset:1856
	ds_write_b32 v240, v56 offset:0
	ds_write_b32 v240, v57 offset:512
	ds_write_b32 v240, v58 offset:1024
	ds_write_b32 v240, v59 offset:1536
	ds_write_b32 v241, v60 offset:0
	ds_write_b32 v241, v61 offset:512
	ds_write_b32 v241, v62 offset:1024
	ds_write_b32 v241, v63 offset:1536
	s_waitcnt lgkmcnt(0)
	ds_read_b128 v[32:35], v242
	ds_read_b128 v[36:39], v242 offset:16
	ds_read_b128 v[40:43], v243
	ds_read_b128 v[44:47], v243 offset:16
	ds_read_b128 v[48:51], v244
	ds_read_b128 v[52:55], v244 offset:16
	ds_read_b128 v[56:59], v245
	ds_read_b128 v[60:63], v245 offset:16
	s_waitcnt vmcnt(13) lgkmcnt(6)
	v_add_f32_e32 v32, v32, v94
	v_add_f32_e32 v33, v33, v94
	v_add_f32_e32 v34, v34, v94
	v_add_f32_e32 v35, v35, v94
	v_add_f32_e32 v36, v36, v94
	v_add_f32_e32 v37, v37, v94
	v_add_f32_e32 v38, v38, v94
	v_add_f32_e32 v39, v39, v94
	v_lshlrev_b32_e32 v98, 16, v190
	v_lshlrev_b32_e32 v99, 16, v191
	v_lshlrev_b32_e32 v100, 16, v192
	v_lshlrev_b32_e32 v101, 16, v193
	v_and_b32_e32 v190, 0xffff0000, v190
	v_and_b32_e32 v191, 0xffff0000, v191
	v_and_b32_e32 v192, 0xffff0000, v192
	v_and_b32_e32 v193, 0xffff0000, v193
	v_mul_f32_e32 v32, v32, v98
	v_mul_f32_e32 v33, v33, v190
	v_mul_f32_e32 v34, v34, v99
	v_mul_f32_e32 v35, v35, v191
	v_mul_f32_e32 v36, v36, v100
	v_mul_f32_e32 v37, v37, v192
	v_mul_f32_e32 v38, v38, v101
	v_mul_f32_e32 v39, v39, v193
	v_lshlrev_b32_e32 v98, 16, v174
	v_lshlrev_b32_e32 v99, 16, v175
	v_lshlrev_b32_e32 v100, 16, v176
	v_lshlrev_b32_e32 v101, 16, v177
	v_and_b32_e32 v174, 0xffff0000, v174
	v_and_b32_e32 v175, 0xffff0000, v175
	v_and_b32_e32 v176, 0xffff0000, v176
	v_and_b32_e32 v177, 0xffff0000, v177
	v_mul_f32_e32 v32, v32, v98
	v_mul_f32_e32 v33, v33, v174
	v_mul_f32_e32 v34, v34, v99
	v_mul_f32_e32 v35, v35, v175
	v_mul_f32_e32 v36, v36, v100
	v_mul_f32_e32 v37, v37, v176
	v_mul_f32_e32 v38, v38, v101
	v_mul_f32_e32 v39, v39, v177
	v_cvt_pk_bf16_f32 v32, v32, v33
	v_cvt_pk_bf16_f32 v33, v34, v35
	v_cvt_pk_bf16_f32 v34, v36, v37
	v_cvt_pk_bf16_f32 v35, v38, v39
	global_store_dwordx4 v236, v[32:35], s[82:83]
	s_add_u32 s82, s82, 0x4000
	s_addc_u32 s83, s83, 0
	s_waitcnt vmcnt(11) lgkmcnt(4)
	v_add_f32_e32 v40, v40, v95
	v_add_f32_e32 v41, v41, v95
	v_add_f32_e32 v42, v42, v95
	v_add_f32_e32 v43, v43, v95
	v_add_f32_e32 v44, v44, v95
	v_add_f32_e32 v45, v45, v95
	v_add_f32_e32 v46, v46, v95
	v_add_f32_e32 v47, v47, v95
	v_lshlrev_b32_e32 v98, 16, v194
	v_lshlrev_b32_e32 v99, 16, v195
	v_lshlrev_b32_e32 v100, 16, v196
	v_lshlrev_b32_e32 v101, 16, v197
	v_and_b32_e32 v194, 0xffff0000, v194
	v_and_b32_e32 v195, 0xffff0000, v195
	v_and_b32_e32 v196, 0xffff0000, v196
	v_and_b32_e32 v197, 0xffff0000, v197
	v_mul_f32_e32 v40, v40, v98
	v_mul_f32_e32 v41, v41, v194
	v_mul_f32_e32 v42, v42, v99
	v_mul_f32_e32 v43, v43, v195
	v_mul_f32_e32 v44, v44, v100
	v_mul_f32_e32 v45, v45, v196
	v_mul_f32_e32 v46, v46, v101
	v_mul_f32_e32 v47, v47, v197
	v_lshlrev_b32_e32 v98, 16, v178
	v_lshlrev_b32_e32 v99, 16, v179
	v_lshlrev_b32_e32 v100, 16, v180
	v_lshlrev_b32_e32 v101, 16, v181
	v_and_b32_e32 v178, 0xffff0000, v178
	v_and_b32_e32 v179, 0xffff0000, v179
	v_and_b32_e32 v180, 0xffff0000, v180
	v_and_b32_e32 v181, 0xffff0000, v181
	v_mul_f32_e32 v40, v40, v98
	v_mul_f32_e32 v41, v41, v178
	v_mul_f32_e32 v42, v42, v99
	v_mul_f32_e32 v43, v43, v179
	v_mul_f32_e32 v44, v44, v100
	v_mul_f32_e32 v45, v45, v180
	v_mul_f32_e32 v46, v46, v101
	v_mul_f32_e32 v47, v47, v181
	v_cvt_pk_bf16_f32 v40, v40, v41
	v_cvt_pk_bf16_f32 v41, v42, v43
	v_cvt_pk_bf16_f32 v42, v44, v45
	v_cvt_pk_bf16_f32 v43, v46, v47
	global_store_dwordx4 v236, v[40:43], s[82:83]
	s_add_u32 s82, s82, 0x4000
	s_addc_u32 s83, s83, 0
	s_waitcnt vmcnt(9) lgkmcnt(2)
	v_add_f32_e32 v48, v48, v96
	v_add_f32_e32 v49, v49, v96
	v_add_f32_e32 v50, v50, v96
	v_add_f32_e32 v51, v51, v96
	v_add_f32_e32 v52, v52, v96
	v_add_f32_e32 v53, v53, v96
	v_add_f32_e32 v54, v54, v96
	v_add_f32_e32 v55, v55, v96
	v_lshlrev_b32_e32 v98, 16, v64
	v_lshlrev_b32_e32 v99, 16, v65
	v_lshlrev_b32_e32 v100, 16, v66
	v_lshlrev_b32_e32 v101, 16, v67
	v_and_b32_e32 v64, 0xffff0000, v64
	v_and_b32_e32 v65, 0xffff0000, v65
	v_and_b32_e32 v66, 0xffff0000, v66
	v_and_b32_e32 v67, 0xffff0000, v67
	v_mul_f32_e32 v48, v48, v98
	v_mul_f32_e32 v49, v49, v64
	v_mul_f32_e32 v50, v50, v99
	v_mul_f32_e32 v51, v51, v65
	v_mul_f32_e32 v52, v52, v100
	v_mul_f32_e32 v53, v53, v66
	v_mul_f32_e32 v54, v54, v101
	v_mul_f32_e32 v55, v55, v67
	v_lshlrev_b32_e32 v98, 16, v182
	v_lshlrev_b32_e32 v99, 16, v183
	v_lshlrev_b32_e32 v100, 16, v184
	v_lshlrev_b32_e32 v101, 16, v185
	v_and_b32_e32 v182, 0xffff0000, v182
	v_and_b32_e32 v183, 0xffff0000, v183
	v_and_b32_e32 v184, 0xffff0000, v184
	v_and_b32_e32 v185, 0xffff0000, v185
	v_mul_f32_e32 v48, v48, v98
	v_mul_f32_e32 v49, v49, v182
	v_mul_f32_e32 v50, v50, v99
	v_mul_f32_e32 v51, v51, v183
	v_mul_f32_e32 v52, v52, v100
	v_mul_f32_e32 v53, v53, v184
	v_mul_f32_e32 v54, v54, v101
	v_mul_f32_e32 v55, v55, v185
	v_cvt_pk_bf16_f32 v48, v48, v49
	v_cvt_pk_bf16_f32 v49, v50, v51
	v_cvt_pk_bf16_f32 v50, v52, v53
	v_cvt_pk_bf16_f32 v51, v54, v55
	global_store_dwordx4 v236, v[48:51], s[82:83]
	s_add_u32 s82, s82, 0x4000
	s_addc_u32 s83, s83, 0
	s_waitcnt vmcnt(7) lgkmcnt(0)
	v_add_f32_e32 v56, v56, v97
	v_add_f32_e32 v57, v57, v97
	v_add_f32_e32 v58, v58, v97
	v_add_f32_e32 v59, v59, v97
	v_add_f32_e32 v60, v60, v97
	v_add_f32_e32 v61, v61, v97
	v_add_f32_e32 v62, v62, v97
	v_add_f32_e32 v63, v63, v97
	v_lshlrev_b32_e32 v98, 16, v68
	v_lshlrev_b32_e32 v99, 16, v69
	v_lshlrev_b32_e32 v100, 16, v70
	v_lshlrev_b32_e32 v101, 16, v71
	v_and_b32_e32 v68, 0xffff0000, v68
	v_and_b32_e32 v69, 0xffff0000, v69
	v_and_b32_e32 v70, 0xffff0000, v70
	v_and_b32_e32 v71, 0xffff0000, v71
	v_mul_f32_e32 v56, v56, v98
	v_mul_f32_e32 v57, v57, v68
	v_mul_f32_e32 v58, v58, v99
	v_mul_f32_e32 v59, v59, v69
	v_mul_f32_e32 v60, v60, v100
	v_mul_f32_e32 v61, v61, v70
	v_mul_f32_e32 v62, v62, v101
	v_mul_f32_e32 v63, v63, v71
	v_lshlrev_b32_e32 v98, 16, v186
	v_lshlrev_b32_e32 v99, 16, v187
	v_lshlrev_b32_e32 v100, 16, v188
	v_lshlrev_b32_e32 v101, 16, v189
	v_and_b32_e32 v186, 0xffff0000, v186
	v_and_b32_e32 v187, 0xffff0000, v187
	v_and_b32_e32 v188, 0xffff0000, v188
	v_and_b32_e32 v189, 0xffff0000, v189
	v_mul_f32_e32 v56, v56, v98
	v_mul_f32_e32 v57, v57, v186
	v_mul_f32_e32 v58, v58, v99
	v_mul_f32_e32 v59, v59, v187
	v_mul_f32_e32 v60, v60, v100
	v_mul_f32_e32 v61, v61, v188
	v_mul_f32_e32 v62, v62, v101
	v_mul_f32_e32 v63, v63, v189
	v_cvt_pk_bf16_f32 v56, v56, v57
	v_cvt_pk_bf16_f32 v57, v58, v59
	v_cvt_pk_bf16_f32 v58, v60, v61
	v_cvt_pk_bf16_f32 v59, v62, v63
	global_store_dwordx4 v236, v[56:59], s[82:83]
	s_add_u32 s82, s82, 0x4000
	s_addc_u32 s83, s83, 0
	s_branch .LBB0_251
